# g12 + P5 selected/window attention: K/V LDS tiles ping-ponged between the two unrolled process copies, one workgroup barrier per tile instead of two
# baseline (speedup 1.0000x reference)
; DI void selwin_item(const Params& p, int it, unsigned char* smem, u16* y_out) {
;     ...
;   for (int pass = 0; pass < 2; ++pass) {
;     const u16* kvp = (const u16*)(p.ws + (pass ? OFF_KVW : OFF_KVS));
;     unsigned rem;
;     if (pass == 0) rem = orm;
;     else { int jlo = (s0 - 511) >> 6; if (jlo < 0) jlo = 0; rem = ((cur >= 31) ? 0xffffffffu : ((2u << cur) - 1u)) & ~((1u << jlo) - 1u); }
;     auto ldtile = [&](u32x4 (&kr)[2], u32x4 (&vr)[2], int j) {
; #pragma unroll
;       for (int i = 0; i < 2; ++i) { const int ch = tid + 256 * i, row = ch >> 3, c = (ch & 7) * 8; const size_t t = tb0 + j * 64 + row;
;         kr[i] = *(const u32x4*)(kvp + t * 512 + g * 64 + c); vr[i] = *(const u32x4*)(kvp + t * 512 + 256 + g * 64 + c); }
;     };
;     auto pop = [&]() { if (!rem) return -1; const int j = __ffs(rem) - 1; rem &= rem - 1; return j; };
;     ...
;     int ja = pop(), jb = pop();
;     if (ja >= 0) ldtile(krA, vrA, ja);
;     if (jb >= 0) ldtile(krB, vrB, jb);
.LBB0_707:
	s_barrier
	s_and_b64 s[0:1], s[34:35], exec
	s_cselect_b32 s0, s55, 0x1bb00800
	s_cselect_b32 s4, s66, s65
	s_add_u32 s0, s42, s0
	s_addc_u32 s1, s43, 0
	s_and_b32 s6, s4, s61
	v_mov_b32_e32 v124, v48
	v_sub_co_u32_e64 v48, s[4:5], s6, 1
	v_mov_b32_e32 v161, v79
	v_mov_b32_e32 v160, v78
	v_mov_b32_e32 v163, v77
	v_mov_b32_e32 v162, v76
	v_mov_b32_e32 v139, v63
	v_mov_b32_e32 v138, v62
	v_mov_b32_e32 v141, v61
	v_mov_b32_e32 v140, v60
	v_mov_b32_e32 v155, v75
	v_mov_b32_e32 v154, v74
	v_mov_b32_e32 v157, v73
	v_mov_b32_e32 v156, v72
	v_mov_b32_e32 v133, v59
	v_mov_b32_e32 v132, v58
	v_mov_b32_e32 v135, v57
	v_mov_b32_e32 v134, v56
	v_mov_b32_e32 v147, v71
	v_mov_b32_e32 v146, v70
	v_mov_b32_e32 v149, v69
	v_mov_b32_e32 v148, v68
	v_mov_b32_e32 v127, v55
	v_mov_b32_e32 v126, v54
	v_mov_b32_e32 v129, v53
	v_mov_b32_e32 v128, v52
	v_mov_b32_e32 v143, v67
	v_mov_b32_e32 v142, v66
	v_mov_b32_e32 v145, v65
	v_mov_b32_e32 v144, v64
	v_mov_b32_e32 v123, v51
	v_mov_b32_e32 v122, v50
	v_mov_b32_e32 v125, v49
	v_readfirstlane_b32 s7, v48
	s_ff1_i32_b32 s8, s6
	s_and_b64 vcc, exec, s[4:5]
	s_cbranch_vccnz .LBB0_709
	s_lshl_b32 s9, s8, 6
	s_or_b32 s26, s9, s60
	v_lshl_add_u64 v[16:17], s[26:27], 0, v[158:159]
	v_lshl_add_u64 v[32:33], s[26:27], 0, v[164:165]
	v_lshlrev_b64 v[16:17], 10, v[16:17]
	v_lshlrev_b64 v[32:33], 10, v[32:33]
	v_lshl_add_u64 v[16:17], s[0:1], 0, v[16:17]
	s_lshl_b32 s10, s62, 1
	s_mov_b32 s11, s27
	v_lshl_add_u64 v[32:33], s[0:1], 0, v[32:33]
	v_lshl_add_u64 v[16:17], v[16:17], 0, s[10:11]
	v_lshl_add_u64 v[32:33], v[32:33], 0, s[10:11]
	v_lshl_add_u64 v[24:25], v[16:17], 0, v[120:121]
	v_lshl_add_u64 v[40:41], v[32:33], 0, v[120:121]
	global_load_dwordx4 v[16:19], v[24:25], off
	s_nop 0
	global_load_dwordx4 v[24:27], v[24:25], off offset:512
	s_nop 0
	global_load_dwordx4 v[32:35], v[40:41], off
	s_nop 0
	global_load_dwordx4 v[40:43], v[40:41], off offset:512

; DI void selwin_item(const Params& p, int it, unsigned char* smem, u16* y_out) {
;     ...
;     auto process = [&](u32x4 (&kr)[2], u32x4 (&vr)[2], int j, int jn) {
;       __syncthreads();
; #pragma unroll
;       for (int i = 0; i < 2; ++i) { const int ch = tid + 256 * i, row = ch >> 3, c = (ch & 7) * 8; *(u32x4*)(Ks + row * KST + c) = kr[i]; *(u32x4*)(Vs + row * KST + c) = vr[i]; }
;       __syncthreads();
;       if (jn >= 0) ldtile(kr, vr, jn);
.LBB0_714:
	s_cmp_lt_i32 s69, 0
	s_cbranch_scc1 .LBB0_712
	v_sub_co_u32_e64 v80, s[44:45], s33, 1
	s_nop 0
	v_readfirstlane_b32 s70, v80
	s_ff1_i32_b32 s67, s33
	s_and_b64 vcc, exec, s[44:45]
	s_waitcnt vmcnt(3)
	ds_write_b128 v166, v[16:19]
	s_waitcnt vmcnt(2)
	ds_write_b128 v166, v[24:27] offset:10240
	s_waitcnt vmcnt(1)
	ds_write_b128 v168, v[32:35]
	s_waitcnt vmcnt(0)
	ds_write_b128 v168, v[40:43] offset:10240
	s_waitcnt lgkmcnt(0)
	s_barrier
	s_cbranch_vccnz .LBB0_717
	s_lshl_b32 s0, s67, 6
	s_or_b32 s26, s0, s60
	v_lshl_add_u64 v[16:17], s[26:27], 0, v[158:159]
	v_lshl_add_u64 v[32:33], s[26:27], 0, v[164:165]
	v_lshlrev_b64 v[16:17], 10, v[16:17]
	v_lshlrev_b64 v[32:33], 10, v[32:33]
	v_lshl_add_u64 v[24:25], v[178:179], 0, v[16:17]
	v_lshl_add_u64 v[40:41], v[178:179], 0, v[32:33]
	global_load_dwordx4 v[16:19], v[24:25], off
	s_nop 0
	global_load_dwordx4 v[24:27], v[24:25], off offset:512
	s_nop 0
	global_load_dwordx4 v[32:35], v[40:41], off
	s_nop 0
	global_load_dwordx4 v[40:43], v[40:41], off offset:512

; DI f32x4 mfma16(bf16x8 a, bf16x8 b, f32x4 c) { return __builtin_amdgcn_mfma_f32_16x16x32_bf16(a, b, c, 0, 0, 0); }
; DI void selwin_item(const Params& p, int it, unsigned char* smem, u16* y_out) {
;     ...
;     auto process = [&](u32x4 (&kr)[2], u32x4 (&vr)[2], int j, int jn) {
;       __syncthreads();
; #pragma unroll
;       for (int i = 0; i < 2; ++i) { const int ch = tid + 256 * i, row = ch >> 3, c = (ch & 7) * 8; *(u32x4*)(Ks + row * KST + c) = kr[i]; *(u32x4*)(Vs + row * KST + c) = vr[i]; }
;       __syncthreads();
;       if (jn >= 0) ldtile(kr, vr, jn);
;       const int k0 = j * 64;
;       f32x4 S[4][2];
; #pragma unroll
;       for (int mt = 0; mt < 4; ++mt) { S[mt][0] = (f32x4){0.f, 0.f, 0.f, 0.f}; S[mt][1] = (f32x4){0.f, 0.f, 0.f, 0.f}; }
;       __builtin_amdgcn_s_setprio(1);
; #pragma unroll
;       for (int mt = 0; mt < 4; ++mt)
; #pragma unroll
;         for (int ks = 0; ks < 2; ++ks) {
;           const bf16x8 a = *(const bf16x8*)(Ks + (mt * 16 + lr) * KST + ks * 32 + lq * 8);
;           S[mt][0] = mfma16(a, qf[0][ks], S[mt][0]); S[mt][1] = mfma16(a, qf[1][ks], S[mt][1]);
;         }
;     ...
;       __builtin_amdgcn_s_setprio(1);
; #pragma unroll
;       for (int kk = 0; kk < 2; ++kk) pv32<2, KST>(O, Vs, kk * 32, 0, pb[kk], lr, lq);
;       __builtin_amdgcn_s_setprio(0);
.LBB0_733:
	v_exp_f32_e32 v83, v199
	s_and_b32 s33, s70, s33
	v_cvt_pk_bf16_f32 v80, v200, v201
	v_cvt_pk_bf16_f32 v81, v194, v195
	v_add_f32_e32 v226, v83, v198
	v_fmac_f32_e32 v226, v225, v180
	v_cvt_pk_bf16_f32 v82, v196, v197
	v_cvt_pk_bf16_f32 v83, v192, v83
	v_cvt_pk_bf16_f32 v84, v184, v185
	v_cvt_pk_bf16_f32 v85, v186, v187
	v_cvt_pk_bf16_f32 v86, v188, v189
	v_cvt_pk_bf16_f32 v87, v190, v191
	s_setprio 1
	ds_read_b64_tr_b16 v[100:101], v167
	ds_read_b64_tr_b16 v[102:103], v167 offset:0xa00
	ds_read_b64_tr_b16 v[96:97], v167 offset:32
	ds_read_b64_tr_b16 v[98:99], v167 offset:0xa20
	ds_read_b64_tr_b16 v[92:93], v167 offset:64
	ds_read_b64_tr_b16 v[94:95], v167 offset:0xa40
	ds_read_b64_tr_b16 v[88:89], v167 offset:96
	ds_read_b64_tr_b16 v[90:91], v167 offset:0xa60
	s_waitcnt lgkmcnt(0)
	s_nop 0
	v_mfma_f32_16x16x32_bf16 v[76:79], v[100:103], v[112:115], v[76:79]
	v_mfma_f32_16x16x32_bf16 v[60:63], v[100:103], v[84:87], v[60:63]
	v_mfma_f32_16x16x32_bf16 v[72:75], v[96:99], v[112:115], v[72:75]
	v_mfma_f32_16x16x32_bf16 v[56:59], v[96:99], v[84:87], v[56:59]
	v_mfma_f32_16x16x32_bf16 v[68:71], v[92:95], v[112:115], v[68:71]
	v_mfma_f32_16x16x32_bf16 v[52:55], v[92:95], v[84:87], v[52:55]
	v_mfma_f32_16x16x32_bf16 v[64:67], v[88:91], v[112:115], v[64:67]
	v_mfma_f32_16x16x32_bf16 v[48:51], v[88:91], v[84:87], v[48:51]
	ds_read_b64_tr_b16 v[96:97], v169
	ds_read_b64_tr_b16 v[98:99], v169 offset:0xa00
	ds_read_b64_tr_b16 v[92:93], v169 offset:32
	ds_read_b64_tr_b16 v[94:95], v169 offset:0xa20
	ds_read_b64_tr_b16 v[88:89], v169 offset:64
	ds_read_b64_tr_b16 v[90:91], v169 offset:0xa40
	ds_read_b64_tr_b16 v[84:85], v169 offset:96
	ds_read_b64_tr_b16 v[86:87], v169 offset:0xa60
	s_waitcnt lgkmcnt(0)
	s_nop 0
	v_mfma_f32_16x16x32_bf16 v[76:79], v[96:99], v[116:119], v[76:79]
	v_mfma_f32_16x16x32_bf16 v[60:63], v[96:99], v[80:83], v[60:63]
	v_mfma_f32_16x16x32_bf16 v[72:75], v[92:95], v[116:119], v[72:75]
	v_mfma_f32_16x16x32_bf16 v[56:59], v[92:95], v[80:83], v[56:59]
	v_mfma_f32_16x16x32_bf16 v[68:71], v[88:91], v[116:119], v[68:71]
	v_mfma_f32_16x16x32_bf16 v[52:55], v[88:91], v[80:83], v[52:55]
	v_mfma_f32_16x16x32_bf16 v[64:67], v[84:87], v[116:119], v[64:67]
	v_mfma_f32_16x16x32_bf16 v[48:51], v[84:87], v[80:83], v[48:51]
	s_setprio 0
	s_cmp_lt_i32 s68, 0
	s_cselect_b64 s[12:13], -1, 0
	s_and_b64 vcc, exec, s[12:13]
	s_cbranch_vccnz .LBB0_740
	v_sub_co_u32_e64 v80, s[14:15], s33, 1
	s_nop 0
	v_readfirstlane_b32 s70, v80
	s_ff1_i32_b32 s69, s33
	s_and_b64 vcc, exec, s[14:15]
	ds_write_b128 v166, v[20:23] offset:24576
	ds_write_b128 v166, v[28:31] offset:34816
	ds_write_b128 v168, v[36:39] offset:24576
	ds_write_b128 v168, v[44:47] offset:34816
	s_waitcnt lgkmcnt(0)
	s_barrier
	s_cbranch_vccnz .LBB0_736
	s_lshl_b32 s0, s69, 6
	s_or_b32 s26, s0, s60
	v_lshl_add_u64 v[20:21], s[26:27], 0, v[158:159]
	v_lshl_add_u64 v[36:37], s[26:27], 0, v[164:165]
	v_lshlrev_b64 v[20:21], 10, v[20:21]
	v_lshlrev_b64 v[36:37], 10, v[36:37]
	v_lshl_add_u64 v[28:29], v[178:179], 0, v[20:21]
	v_lshl_add_u64 v[44:45], v[178:179], 0, v[36:37]
	global_load_dwordx4 v[20:23], v[28:29], off
	s_nop 0
	global_load_dwordx4 v[28:31], v[28:29], off offset:512
	s_nop 0
	global_load_dwordx4 v[36:39], v[44:45], off
	s_nop 0
	global_load_dwordx4 v[44:47], v[44:45], off offset:512
.LBB0_736:
	s_setprio 1
	ds_read_b128 v[80:83], v215 offset:24576
	ds_read_b128 v[84:87], v215 offset:24640
	ds_read_b128 v[88:91], v215 offset:27136
	s_lshl_b32 s0, s68, 6
	s_sub_i32 s8, 0, s0
	s_waitcnt lgkmcnt(2)
	v_mfma_f32_16x16x32_bf16 v[92:95], v[80:83], v[4:7], 0
	v_mfma_f32_16x16x32_bf16 v[80:83], v[80:83], v[12:15], 0
	ds_read_b128 v[96:99], v215 offset:27200
	s_waitcnt lgkmcnt(2)
	v_mfma_f32_16x16x32_bf16 v[108:111], v[84:87], v[8:11], v[92:95]
	v_mfma_f32_16x16x32_bf16 v[92:95], v[84:87], v[0:3], v[80:83]
	s_nop 3
	ds_read_b128 v[80:83], v215 offset:29696
	s_waitcnt lgkmcnt(2)
	v_mfma_f32_16x16x32_bf16 v[84:87], v[88:91], v[4:7], 0
	v_mfma_f32_16x16x32_bf16 v[88:91], v[88:91], v[12:15], 0
	ds_read_b128 v[112:115], v215 offset:29760
	s_waitcnt lgkmcnt(2)
	v_mfma_f32_16x16x32_bf16 v[104:107], v[96:99], v[8:11], v[84:87]
	v_mfma_f32_16x16x32_bf16 v[88:91], v[96:99], v[0:3], v[88:91]
	ds_read_b128 v[96:99], v215 offset:32256
	s_waitcnt lgkmcnt(2)
	v_mfma_f32_16x16x32_bf16 v[84:87], v[80:83], v[4:7], 0
	v_mfma_f32_16x16x32_bf16 v[80:83], v[80:83], v[12:15], 0
	ds_read_b128 v[116:119], v215 offset:32320
	s_waitcnt lgkmcnt(2)
	v_mfma_f32_16x16x32_bf16 v[100:103], v[112:115], v[8:11], v[84:87]
	v_mfma_f32_16x16x32_bf16 v[84:87], v[112:115], v[0:3], v[80:83]
	s_waitcnt lgkmcnt(1)
	v_mfma_f32_16x16x32_bf16 v[80:83], v[96:99], v[4:7], 0
	v_mfma_f32_16x16x32_bf16 v[112:115], v[96:99], v[12:15], 0
	s_waitcnt lgkmcnt(0)
	v_mfma_f32_16x16x32_bf16 v[96:99], v[116:119], v[8:11], v[80:83]
	v_mfma_f32_16x16x32_bf16 v[80:83], v[116:119], v[0:3], v[112:115]
	s_setprio 0
	s_sub_i32 s0, s63, s0
	s_cmpk_lt_i32 s0, 0x71
	s_cselect_b64 s[0:1], -1, 0
	s_and_b64 vcc, exec, s[0:1]
	s_cbranch_vccnz .LBB0_741
	s_add_i32 s4, s8, s64
	s_cmpk_gt_i32 s4, 0x1ff
	s_cselect_b64 s[6:7], -1, 0
	s_mov_b64 s[4:5], -1
	s_and_b64 s[6:7], s[36:37], s[6:7]
	s_andn2_b64 vcc, exec, s[6:7]
	s_cbranch_vccz .LBB0_742

; DI f32x4 mfma16(bf16x8 a, bf16x8 b, f32x4 c) { return __builtin_amdgcn_mfma_f32_16x16x32_bf16(a, b, c, 0, 0, 0); }
; template <int NT, int VST> DI void pv32(f32x4 (&O)[4][NT], const u16* Vs, int krow, int dcol, const bf16x8 (&pb)[NT], int lr, int lq) {
;   const unsigned addr = (unsigned)(size_t)(Vs + (krow + 4 * lq + (lr >> 2)) * VST + dcol + 4 * (lr & 3));
;   s16x4 lo[4], hi[4];
;   tr8<VST * 2>(addr, lo, hi);
; #pragma unroll
;   for (int dt = 0; dt < 4; ++dt) {
;     const bf16x8 a = __builtin_shufflevector(lo[dt], hi[dt], 0, 1, 2, 3, 4, 5, 6, 7);
; #pragma unroll
;     for (int nt = 0; nt < NT; ++nt) O[dt][nt] = mfma16(a, pb[nt], O[dt][nt]);
;   }
; DI void selwin_item(const Params& p, int it, unsigned char* smem, u16* y_out) {
;     ...
;       __builtin_amdgcn_s_setprio(1);
; #pragma unroll
;       for (int kk = 0; kk < 2; ++kk) pv32<2, KST>(O, Vs, kk * 32, 0, pb[kk], lr, lq);
;       __builtin_amdgcn_s_setprio(0);
.LBB0_753:
	v_exp_f32_e32 v83, v199
	s_and_b32 s33, s70, s33
	s_and_b64 s[0:1], exec, s[14:15]
	s_cselect_b32 s68, -1, s69
	s_and_b64 s[0:1], exec, s[44:45]
	v_add_f32_e32 v104, v83, v198
	s_cselect_b32 s69, -1, s67
	v_fmac_f32_e32 v104, v226, v180
	v_cvt_pk_bf16_f32 v80, v200, v201
	v_cvt_pk_bf16_f32 v81, v194, v195
	v_cvt_pk_bf16_f32 v82, v196, v197
	v_cvt_pk_bf16_f32 v83, v192, v83
	v_cvt_pk_bf16_f32 v84, v184, v185
	v_cvt_pk_bf16_f32 v85, v186, v187
	v_cvt_pk_bf16_f32 v86, v188, v189
	v_cvt_pk_bf16_f32 v87, v190, v191
	s_setprio 1
	ds_read_b64_tr_b16 v[100:101], v167 offset:24576
	ds_read_b64_tr_b16 v[102:103], v167 offset:27136
	ds_read_b64_tr_b16 v[96:97], v167 offset:24608
	ds_read_b64_tr_b16 v[98:99], v167 offset:27168
	ds_read_b64_tr_b16 v[92:93], v167 offset:24640
	ds_read_b64_tr_b16 v[94:95], v167 offset:27200
	ds_read_b64_tr_b16 v[88:89], v167 offset:24672
	ds_read_b64_tr_b16 v[90:91], v167 offset:27232
	s_waitcnt lgkmcnt(0)
	s_nop 0
	v_mfma_f32_16x16x32_bf16 v[76:79], v[100:103], v[112:115], v[76:79]
	v_mfma_f32_16x16x32_bf16 v[60:63], v[100:103], v[84:87], v[60:63]
	v_mfma_f32_16x16x32_bf16 v[72:75], v[96:99], v[112:115], v[72:75]
	v_mfma_f32_16x16x32_bf16 v[56:59], v[96:99], v[84:87], v[56:59]
	v_mfma_f32_16x16x32_bf16 v[68:71], v[92:95], v[112:115], v[68:71]
	v_mfma_f32_16x16x32_bf16 v[52:55], v[92:95], v[84:87], v[52:55]
	v_mfma_f32_16x16x32_bf16 v[64:67], v[88:91], v[112:115], v[64:67]
	v_mfma_f32_16x16x32_bf16 v[48:51], v[88:91], v[84:87], v[48:51]
	ds_read_b64_tr_b16 v[96:97], v169 offset:24576
	ds_read_b64_tr_b16 v[98:99], v169 offset:27136
	ds_read_b64_tr_b16 v[92:93], v169 offset:24608
	ds_read_b64_tr_b16 v[94:95], v169 offset:27168
	ds_read_b64_tr_b16 v[88:89], v169 offset:24640
	ds_read_b64_tr_b16 v[90:91], v169 offset:27200
	ds_read_b64_tr_b16 v[84:85], v169 offset:24672
	ds_read_b64_tr_b16 v[86:87], v169 offset:27232
	s_waitcnt lgkmcnt(0)
	s_nop 0
	v_mfma_f32_16x16x32_bf16 v[76:79], v[96:99], v[116:119], v[76:79]
	v_mfma_f32_16x16x32_bf16 v[60:63], v[96:99], v[80:83], v[60:63]
	v_mfma_f32_16x16x32_bf16 v[72:75], v[92:95], v[116:119], v[72:75]
	v_mfma_f32_16x16x32_bf16 v[56:59], v[92:95], v[80:83], v[56:59]
	v_mfma_f32_16x16x32_bf16 v[68:71], v[88:91], v[116:119], v[68:71]
	v_mfma_f32_16x16x32_bf16 v[52:55], v[88:91], v[80:83], v[52:55]
	v_mfma_f32_16x16x32_bf16 v[64:67], v[84:87], v[116:119], v[64:67]
	v_mfma_f32_16x16x32_bf16 v[48:51], v[84:87], v[80:83], v[48:51]
	s_setprio 0
	v_mov_b32_e32 v225, v104
	s_branch .LBB0_713
